# waves 4-7 run the class-2 w_in conversion before the DeltaNet prep (P2/P3), waves 0-3 after: memory-streaming wave pairs with latency-bound wave on each SIMD
# baseline (speedup 1.0000x reference)
_Z6mk_fwd4Args:
	s_mov_b32 s100, 0
	s_load_dwordx8 s[4:11], s[0:1], 0x80
	v_mov_b32_e32 v1, v0
	s_mov_b32 s81, s2
	s_add_u32 s2, s0, 0xb8
	s_waitcnt lgkmcnt(0)
	v_writelane_b32 v251, s4, 0
	s_addc_u32 s3, s1, 0
	s_nop 0
	v_writelane_b32 v251, s5, 1
	v_writelane_b32 v251, s6, 2
	v_writelane_b32 v251, s7, 3
	v_writelane_b32 v251, s8, 4
	v_writelane_b32 v251, s9, 5
	v_writelane_b32 v251, s10, 6
	v_writelane_b32 v251, s11, 7
	s_load_dword s82, s[0:1], 0xb8
	s_load_dwordx2 s[94:95], s[0:1], 0xa0
	s_load_dwordx4 s[4:7], s[0:1], 0xa8
	s_waitcnt lgkmcnt(0)
	v_writelane_b32 v251, s4, 8
	s_nop 1
	v_writelane_b32 v251, s5, 9
	v_writelane_b32 v251, s6, 10
	v_writelane_b32 v251, s7, 11
	v_writelane_b32 v251, s2, 12
	v_readfirstlane_b32 s6, v1
	s_mov_b32 s7, s81
	v_writelane_b32 v251, s3, 13
	s_and_b32 s2, s82, 7
	s_cmp_lg_u32 s2, 0
	s_cbranch_scc0 .LBB0_2
	s_movk_i32 s2, 0x400
	v_cmp_gt_i32_e32 vcc, s2, v1
	s_and_saveexec_b64 s[2:3], vcc
	s_cbranch_execnz .LBB0_3
	s_branch .LBB0_5

.LBB0_179:
	s_cmp_lt_u32 s50, 4
	s_cbranch_scc1 .Lstag_skip
	s_mov_b64 s[98:99], s[2:3]
	s_mov_b32 s100, 1
	s_mov_b32 s59, s50
	s_mul_i32 s87, s50, 0x4600
	v_mov_b32_e32 v119, v0
	v_and_b32_e32 v128, 63, v0
	s_branch .LBB0_288
.Lstag_ret:
	s_mov_b64 s[2:3], s[98:99]
	s_mov_b32 s50, s59
	s_mov_b32 s100, 2

.LBB0_288:
	s_mov_b32 s50, s59
	s_cmp_eq_u32 s100, 2
	s_cbranch_scc1 .LBB0_311
	s_cmp_gt_i32 s90, 0xc83f
	s_mov_b32 s50, s59
	s_cbranch_scc1 .Lstag_exit
	s_lshl_b32 s1, s90, 5
	s_lshl_b32 s7, s92, 5
	s_movk_i32 s8, 0xd400
	s_mov_b32 s10, s90
	s_branch .LBB0_291

.Lstag_exit:
	s_cmp_eq_u32 s100, 1
	s_cbranch_scc1 .Lstag_ret

	.amdhsa_kernel _Z6mk_fwd4Args
		.amdhsa_group_segment_fixed_size 0
		.amdhsa_private_segment_fixed_size 0
		.amdhsa_kernarg_size 440
		.amdhsa_user_sgpr_count 2
		.amdhsa_user_sgpr_dispatch_ptr 0
		.amdhsa_user_sgpr_queue_ptr 0
		.amdhsa_user_sgpr_kernarg_segment_ptr 1
		.amdhsa_user_sgpr_dispatch_id 0
		.amdhsa_user_sgpr_kernarg_preload_length 0
		.amdhsa_user_sgpr_kernarg_preload_offset 0
		.amdhsa_user_sgpr_private_segment_size 0
		.amdhsa_uses_dynamic_stack 0
		.amdhsa_enable_private_segment 0
		.amdhsa_system_sgpr_workgroup_id_x 1
		.amdhsa_system_sgpr_workgroup_id_y 0
		.amdhsa_system_sgpr_workgroup_id_z 0
		.amdhsa_system_sgpr_workgroup_info 0
		.amdhsa_system_vgpr_workitem_id 0
		.amdhsa_next_free_vgpr 252
		.amdhsa_next_free_sgpr 102
		.amdhsa_accum_offset 252
		.amdhsa_reserve_vcc 1
		.amdhsa_float_round_mode_32 0
		.amdhsa_float_round_mode_16_64 0
		.amdhsa_float_denorm_mode_32 3
		.amdhsa_float_denorm_mode_16_64 3
		.amdhsa_dx10_clamp 1
		.amdhsa_ieee_mode 1
		.amdhsa_fp16_overflow 0
		.amdhsa_tg_split 0
		.amdhsa_exception_fp_ieee_invalid_op 0
		.amdhsa_exception_fp_denorm_src 0
		.amdhsa_exception_fp_ieee_div_zero 0
		.amdhsa_exception_fp_ieee_overflow 0
		.amdhsa_exception_fp_ieee_underflow 0
		.amdhsa_exception_fp_ieee_inexact 0
		.amdhsa_exception_int_div_zero 0
	.end_amdhsa_kernel

amdhsa.kernels:
  - .agpr_count:     0
    .args:
      - .offset:         0
        .size:           184
        .value_kind:     by_value
      - .offset:         184
        .size:           4
        .value_kind:     hidden_block_count_x
      - .offset:         188
        .size:           4
        .value_kind:     hidden_block_count_y
      - .offset:         192
        .size:           4
        .value_kind:     hidden_block_count_z
      - .offset:         196
        .size:           2
        .value_kind:     hidden_group_size_x
      - .offset:         198
        .size:           2
        .value_kind:     hidden_group_size_y
      - .offset:         200
        .size:           2
        .value_kind:     hidden_group_size_z
      - .offset:         202
        .size:           2
        .value_kind:     hidden_remainder_x
      - .offset:         204
        .size:           2
        .value_kind:     hidden_remainder_y
      - .offset:         206
        .size:           2
        .value_kind:     hidden_remainder_z
      - .offset:         224
        .size:           8
        .value_kind:     hidden_global_offset_x
      - .offset:         232
        .size:           8
        .value_kind:     hidden_global_offset_y
      - .offset:         240
        .size:           8
        .value_kind:     hidden_global_offset_z
      - .offset:         248
        .size:           2
        .value_kind:     hidden_grid_dims
      - .offset:         304
        .size:           4
        .value_kind:     hidden_dynamic_lds_size
    .group_segment_fixed_size: 0
    .kernarg_segment_align: 8
    .kernarg_segment_size: 440
    .language:       OpenCL C
    .language_version:
      - 2
      - 0
    .max_flat_workgroup_size: 512
    .name:           _Z6mk_fwd4Args
    .private_segment_fixed_size: 0
    .sgpr_count:     108
    .sgpr_spill_count: 75
    .symbol:         _Z6mk_fwd4Args.kd
    .uniform_work_group_size: 1
    .uses_dynamic_stack: false
    .vgpr_count:     252
    .vgpr_spill_count: 0
    .wavefront_size: 64
